# P3 loop: tile bias folded into the QK SrcC block (rebuilt for the next tile in the idle p0-chain VALU slots); p0 bias adds removed, p1 uses a constant subtract
# speedup vs baseline: 1.0163x; 1.0151x over previous
.LBB0_316:
	s_or_b64 exec, exec, s[0:1]
	s_add_i32 s0, s95, 1
	v_cvt_f32_ubyte0_e32 v1, s0
	s_mov_b32 s0, 0x42fc0000
	v_cmp_lt_f32_e32 vcc, s0, v1
	s_and_b64 s[0:1], vcc, exec
	s_cselect_b32 s0, 0xffffffc0, 0
	v_cndmask_b32_e32 v4, 0, v227, vcc
	v_sub_f32_e32 v1, v4, v1
	v_exp_f32_e32 v1, v1
	v_lshlrev_b32_e32 v34, 2, v2
	v_lshrrev_b32_e32 v37, 1, v0
	s_lshl_b32 s77, s75, 15
	v_ldexp_f32 v1, v1, s0
	v_mul_f32_e32 v208, 0x3fb8aa3b, v1
	v_sub_u32_e32 v1, v34, v3
	v_cvt_f32_i32_e32 v255, v1
	v_add_u32_e32 v10, 10, v1
	v_add_u32_e32 v11, 11, v1
	v_cvt_f32_i32_e32 v11, v11
	v_cvt_f32_i32_e32 v10, v10
	v_readlane_b32 s0, v244, 17
	v_bitop3_b32 v0, v37, v2, 7 bitop3:0x6c
	s_add_i32 s76, s77, 0
	v_lshl_or_b32 v36, v32, 7, s0
	v_pk_mul_f32 v[70:71], v[208:209], v[10:11] op_sel_hi:[0,1]
	v_lshlrev_b32_e32 v230, 4, v0
	v_add_u32_e32 v10, s76, v36
	v_add_u32_e32 v3, 1, v1
	v_add_u32_e32 v11, v10, v230
	v_xor_b32_e32 v231, 32, v230
	v_add_u32_e32 v6, 2, v1
	v_add_u32_e32 v7, 3, v1
	v_add_u32_e32 v8, 8, v1
	v_add_u32_e32 v9, 9, v1
	v_add_u32_e32 v12, 16, v1
	v_add_u32_e32 v13, 17, v1
	v_add_u32_e32 v14, 18, v1
	v_add_u32_e32 v15, 19, v1
	v_add_u32_e32 v16, 24, v1
	v_add_u32_e32 v17, 25, v1
	v_add_u32_e32 v18, 26, v1
	v_add_u32_e32 v19, 27, v1
	v_cvt_f32_i32_e32 v4, v1
	v_cvt_f32_i32_e32 v5, v3
	ds_read_b128 v[0:3], v11 offset:16384
	ds_read_b128 v[40:43], v11 offset:20480
	v_add_u32_e32 v11, v10, v231
	v_xor_b32_e32 v232, 64, v230
	v_xor_b32_e32 v233, 0x60, v230
	ds_read_b128 v[44:47], v11 offset:16384
	ds_read_b128 v[48:51], v11 offset:20480
	v_add_u32_e32 v11, v10, v232
	v_add_u32_e32 v10, v10, v233
	v_cvt_f32_i32_e32 v7, v7
	v_cvt_f32_i32_e32 v6, v6
	v_cvt_f32_i32_e32 v9, v9
	v_cvt_f32_i32_e32 v8, v8
	v_cvt_f32_i32_e32 v13, v13
	v_cvt_f32_i32_e32 v15, v15
	v_cvt_f32_i32_e32 v17, v17
	v_cvt_f32_i32_e32 v19, v19
	v_cvt_f32_i32_e32 v18, v18
	v_cvt_f32_i32_e32 v16, v16
	v_cvt_f32_i32_e32 v14, v14
	v_cvt_f32_i32_e32 v12, v12
	ds_read_b128 v[52:55], v11 offset:16384
	ds_read_b128 v[56:59], v11 offset:20480
	ds_read_b128 v[60:63], v10 offset:16384
	ds_read_b128 v[80:83], v10 offset:20480
	v_pk_mul_f32 v[78:79], v[208:209], v[18:19] op_sel_hi:[0,1]
	v_pk_mul_f32 v[76:77], v[208:209], v[16:17] op_sel_hi:[0,1]
	v_pk_mul_f32 v[74:75], v[208:209], v[14:15] op_sel_hi:[0,1]
	v_pk_mul_f32 v[72:73], v[208:209], v[12:13] op_sel_hi:[0,1]
	v_pk_mul_f32 v[68:69], v[208:209], v[8:9] op_sel_hi:[0,1]
	v_pk_mul_f32 v[66:67], v[208:209], v[6:7] op_sel_hi:[0,1]
	v_pk_mul_f32 v[64:65], v[208:209], v[4:5] op_sel_hi:[0,1]
	s_or_b32 s78, s2, s34
	s_waitcnt lgkmcnt(7)
	v_mfma_f32_32x32x16_bf16 v[16:31], v[0:3], v[144:147], v[64:79]
	s_waitcnt lgkmcnt(6)
	v_mfma_f32_32x32x16_bf16 v[0:15], v[40:43], v[144:147], v[64:79]
	s_waitcnt lgkmcnt(5)
	v_mfma_f32_32x32x16_bf16 v[16:31], v[44:47], v[140:143], v[16:31]
	s_waitcnt lgkmcnt(4)
	v_mfma_f32_32x32x16_bf16 v[0:15], v[48:51], v[140:143], v[0:15]
	s_waitcnt lgkmcnt(3)
	v_mfma_f32_32x32x16_bf16 v[16:31], v[52:55], v[136:139], v[16:31]
	s_waitcnt lgkmcnt(2)
	v_mfma_f32_32x32x16_bf16 v[0:15], v[56:59], v[136:139], v[0:15]
	s_waitcnt lgkmcnt(1)
	v_mfma_f32_32x32x16_bf16 v[16:31], v[60:63], v[132:135], v[16:31]
	s_waitcnt lgkmcnt(0)
	v_mfma_f32_32x32x16_bf16 v[0:15], v[80:83], v[132:135], v[0:15]
	s_and_b32 s72, s3, 0x7fffffc0
	s_or_b32 s0, s3, 63
	s_cmp_le_u32 s0, s78
	v_writelane_b32 v244, s10, 32
	s_cbranch_scc1 .LBB0_318
	v_or_b32_e32 v39, s72, v34
	v_sub_u32_e32 v38, v38, v39
	v_cmp_gt_i32_e64 s[60:61], 26, v38
	v_cmp_gt_i32_e64 s[62:63], 27, v38
	v_cmp_gt_i32_e64 s[58:59], 25, v38
	s_and_b64 s[60:61], s[62:63], s[60:61]
	v_cmp_gt_i32_e64 s[56:57], 24, v38
	s_and_b64 s[58:59], s[60:61], s[58:59]
	v_cmp_gt_i32_e64 s[54:55], 19, v38
	s_and_b64 s[56:57], s[58:59], s[56:57]
	v_cmp_gt_i32_e64 s[52:53], 18, v38
	s_and_b64 s[54:55], s[56:57], s[54:55]
	v_cmp_gt_i32_e64 s[50:51], 17, v38
	s_and_b64 s[52:53], s[54:55], s[52:53]
	v_cmp_gt_i32_e64 s[48:49], 16, v38
	s_and_b64 s[50:51], s[52:53], s[50:51]
	v_cmp_gt_i32_e64 s[46:47], 11, v38
	s_and_b64 s[48:49], s[50:51], s[48:49]
	v_cmp_gt_i32_e64 s[44:45], 10, v38
	s_and_b64 s[46:47], s[48:49], s[46:47]
	v_cmp_gt_i32_e64 s[42:43], 9, v38
	s_and_b64 s[44:45], s[46:47], s[44:45]
	v_cmp_gt_i32_e64 s[40:41], 8, v38
	s_and_b64 s[42:43], s[44:45], s[42:43]
	v_cmp_gt_i32_e64 s[38:39], 3, v38
	s_and_b64 s[40:41], s[42:43], s[40:41]
	v_cmp_gt_i32_e64 s[36:37], 2, v38
	s_and_b64 s[38:39], s[40:41], s[38:39]
	v_cmp_gt_i32_e64 s[34:35], 1, v38
	s_and_b64 s[36:37], s[38:39], s[36:37]
	v_cmp_gt_i32_e64 s[30:31], 0, v38
	s_and_b64 s[34:35], s[36:37], s[34:35]
	s_and_b64 s[30:31], s[34:35], s[30:31]
	v_cmp_gt_i32_e64 s[28:29], 58, v38
	v_cndmask_b32_e64 v16, v16, v228, s[30:31]
	v_cmp_gt_i32_e64 s[30:31], 59, v38
	v_cmp_gt_i32_e64 s[26:27], 57, v38
	s_and_b64 s[28:29], s[30:31], s[28:29]
	v_cmp_gt_i32_e64 s[24:25], 56, v38
	s_and_b64 s[26:27], s[28:29], s[26:27]
	v_cmp_gt_i32_e64 s[22:23], 51, v38
	s_and_b64 s[24:25], s[26:27], s[24:25]
	v_cmp_gt_i32_e64 s[20:21], 50, v38
	s_and_b64 s[22:23], s[24:25], s[22:23]
	v_cmp_gt_i32_e64 s[18:19], 49, v38
	s_and_b64 s[20:21], s[22:23], s[20:21]
	v_cmp_gt_i32_e64 s[16:17], 48, v38
	s_and_b64 s[18:19], s[20:21], s[18:19]
	v_cmp_gt_i32_e64 s[14:15], 43, v38
	s_and_b64 s[16:17], s[18:19], s[16:17]
	v_cmp_gt_i32_e64 s[12:13], 42, v38
	s_and_b64 s[14:15], s[16:17], s[14:15]
	v_cmp_gt_i32_e64 s[10:11], 41, v38
	s_and_b64 s[12:13], s[14:15], s[12:13]
	v_cmp_gt_i32_e64 s[8:9], 40, v38
	s_and_b64 s[10:11], s[12:13], s[10:11]
	v_cmp_gt_i32_e64 s[6:7], 35, v38
	s_and_b64 s[8:9], s[10:11], s[8:9]
	v_cmp_gt_i32_e64 s[4:5], 34, v38
	s_and_b64 s[6:7], s[8:9], s[6:7]
	v_cmp_gt_i32_e64 s[0:1], 33, v38
	s_and_b64 s[4:5], s[6:7], s[4:5]
	v_cmp_gt_i32_e32 vcc, 32, v38
	s_and_b64 s[0:1], s[4:5], s[0:1]
	s_and_b64 vcc, s[0:1], vcc
	v_cndmask_b32_e64 v31, v31, v228, s[62:63]
	v_cndmask_b32_e64 v30, v30, v228, s[60:61]
	v_cndmask_b32_e64 v29, v29, v228, s[58:59]
	v_cndmask_b32_e64 v28, v28, v228, s[56:57]
	v_cndmask_b32_e64 v27, v27, v228, s[54:55]
	v_cndmask_b32_e64 v26, v26, v228, s[52:53]
	v_cndmask_b32_e64 v25, v25, v228, s[50:51]
	v_cndmask_b32_e64 v24, v24, v228, s[48:49]
	v_cndmask_b32_e64 v23, v23, v228, s[46:47]
	v_cndmask_b32_e64 v22, v22, v228, s[44:45]
	v_cndmask_b32_e64 v21, v21, v228, s[42:43]
	v_cndmask_b32_e64 v20, v20, v228, s[40:41]
	v_cndmask_b32_e64 v19, v19, v228, s[38:39]
	v_cndmask_b32_e64 v18, v18, v228, s[36:37]
	v_cndmask_b32_e64 v17, v17, v228, s[34:35]
	v_cndmask_b32_e64 v15, v15, v228, s[30:31]
	v_cndmask_b32_e64 v14, v14, v228, s[28:29]
	v_cndmask_b32_e64 v13, v13, v228, s[26:27]
	v_cndmask_b32_e64 v12, v12, v228, s[24:25]
	v_cndmask_b32_e64 v11, v11, v228, s[22:23]
	v_cndmask_b32_e64 v10, v10, v228, s[20:21]
	v_cndmask_b32_e64 v9, v9, v228, s[18:19]
	v_cndmask_b32_e64 v8, v8, v228, s[16:17]
	v_cndmask_b32_e64 v7, v7, v228, s[14:15]
	v_cndmask_b32_e64 v6, v6, v228, s[12:13]
	v_cndmask_b32_e64 v5, v5, v228, s[10:11]
	v_cndmask_b32_e64 v4, v4, v228, s[8:9]
	v_cndmask_b32_e64 v3, v3, v228, s[6:7]
	v_cndmask_b32_e64 v2, v2, v228, s[4:5]
	v_cndmask_b32_e64 v1, v1, v228, s[0:1]
	v_cndmask_b32_e32 v0, v0, v228, vcc
.LBB0_318:
	s_or_b32 s0, s78, 31
	s_or_b32 s1, s2, 64
	s_cmp_gt_u32 s1, s0
	s_cselect_b64 s[70:71], -1, 0
	s_cmp_lg_u64 s[70:71], 0
	s_subb_u32 s82, s33, 0
	s_sub_i32 s0, s72, s2
	v_cvt_f32_i32_e32 v38, s0
	v_lshrrev_b32_e32 v35, 2, v35
	v_lshlrev_b32_e32 v45, 1, v211
	v_and_b32_e32 v44, 12, v33
	v_fma_f32 v40, v208, v38, -v207
	v_fmamk_f32 v41, v208, 0x42000000, v40
	v_add_f32_e32 v16, v40, v16
	v_add_f32_e32 v0, v41, v0
	v_exp_f32_e32 v42, v16
	v_exp_f32_e32 v43, v0
	v_add_f32_e32 v0, v40, v17
	v_add_f32_e32 v1, v41, v1
	v_exp_f32_e32 v0, v0
	v_exp_f32_e32 v16, v1
	v_add_f32_e32 v17, v43, v42
	v_mov_b32_e32 v1, v113
	v_add_f32_e32 v2, v41, v2
	v_pk_add_f32 v[38:39], v[16:17], v[0:1]
	v_add_f32_e32 v1, v40, v18
	v_pk_add_f32 v[38:39], v[38:39], v[38:39] op_sel_hi:[0,1]
	v_exp_f32_e32 v17, v2
	v_add_f32_e32 v2, v40, v19
	v_exp_f32_e32 v1, v1
	v_exp_f32_e32 v38, v2
	v_add_f32_e32 v2, v41, v3
	v_exp_f32_e32 v2, v2
	v_add_f32_e32 v3, v17, v1
	v_add_f32_e32 v4, v41, v4
	v_add_f32_e32 v6, v41, v6
	v_pk_add_f32 v[18:19], v[2:3], v[38:39]
	v_add_f32_e32 v3, v40, v20
	v_pk_add_f32 v[18:19], v[18:19], v[18:19] op_sel_hi:[0,1]
	v_exp_f32_e32 v39, v4
	v_add_f32_e32 v4, v40, v21
	v_exp_f32_e32 v3, v3
	v_exp_f32_e32 v18, v4
	v_add_f32_e32 v4, v41, v5
	v_exp_f32_e32 v4, v4
	v_or_b32_e32 v5, v34, v35
	v_lshlrev_b32_e32 v35, 8, v5
	v_add_f32_e32 v5, v39, v3
	v_pk_add_f32 v[20:21], v[4:5], v[18:19]
	v_add_f32_e32 v5, v40, v22
	v_pk_add_f32 v[20:21], v[20:21], v[20:21] op_sel_hi:[0,1]
	v_exp_f32_e32 v19, v6
	v_add_f32_e32 v6, v40, v23
	v_exp_f32_e32 v5, v5
	v_exp_f32_e32 v20, v6
	v_add_f32_e32 v6, v41, v7
	v_exp_f32_e32 v6, v6
	v_add_f32_e32 v7, v19, v5
	v_add_f32_e32 v8, v41, v8
	v_add_f32_e32 v10, v41, v10
	v_pk_add_f32 v[22:23], v[6:7], v[20:21]
	v_add_f32_e32 v7, v40, v24
	v_pk_add_f32 v[22:23], v[22:23], v[22:23] op_sel_hi:[0,1]
	v_exp_f32_e32 v21, v8
	v_add_f32_e32 v8, v40, v25
	v_exp_f32_e32 v7, v7
	v_exp_f32_e32 v22, v8
	v_add_f32_e32 v8, v41, v9
	v_exp_f32_e32 v8, v8
	v_add_f32_e32 v9, v21, v7
	v_and_b32_e32 v45, 2, v45
	v_and_b32_e32 v37, 1, v37
	v_pk_add_f32 v[24:25], v[8:9], v[22:23]
	v_add_f32_e32 v9, v40, v26
	v_pk_add_f32 v[24:25], v[24:25], v[24:25] op_sel_hi:[0,1]
	v_exp_f32_e32 v23, v10
	v_add_f32_e32 v10, v40, v27
	v_exp_f32_e32 v9, v9
	v_exp_f32_e32 v24, v10
	v_add_f32_e32 v10, v41, v11
	v_exp_f32_e32 v10, v10
	v_or3_b32 v11, v44, v45, v37
	v_lshlrev_b32_e32 v37, 4, v11
	v_add_f32_e32 v11, v23, v9
	v_pk_add_f32 v[26:27], v[10:11], v[24:25]
	v_add_f32_e32 v12, v41, v12
	v_pk_add_f32 v[26:27], v[26:27], v[26:27] op_sel_hi:[0,1]
	v_add_f32_e32 v11, v40, v28
	v_exp_f32_e32 v25, v12
	v_add_f32_e32 v12, v40, v29
	v_exp_f32_e32 v11, v11
	v_exp_f32_e32 v26, v12
	v_add_f32_e32 v12, v41, v13
	v_exp_f32_e32 v12, v12
	v_lshlrev_b32_e32 v13, 3, v33
	v_and_b32_e32 v33, 8, v13
	v_add_f32_e32 v13, v25, v11
	v_pk_add_f32 v[28:29], v[12:13], v[26:27]
	v_add_f32_e32 v14, v41, v14
	v_pk_add_f32 v[28:29], v[28:29], v[28:29] op_sel_hi:[0,1]
	v_add_f32_e32 v13, v40, v30
	v_exp_f32_e32 v27, v14
	v_add_f32_e32 v14, v40, v31
	v_exp_f32_e32 v13, v13
	v_exp_f32_e32 v28, v14
	v_add_f32_e32 v14, v41, v15
	v_exp_f32_e32 v14, v14
	v_add_f32_e32 v15, v27, v13
	v_or3_b32 v235, v37, v35, v33
	s_mov_b32 s72, 0
	v_pk_add_f32 v[30:31], v[14:15], v[28:29]
	v_cvt_pk_bf16_f32 v152, v42, v0
	v_cvt_pk_bf16_f32 v153, v1, v38
	v_cvt_pk_bf16_f32 v154, v3, v18
	v_cvt_pk_bf16_f32 v155, v5, v20
	v_cvt_pk_bf16_f32 v156, v7, v22
	s_nop 0
	v_add_f32_e32 v15, v30, v31
	v_add_f32_e32 v229, 0, v15
	v_cvt_pk_bf16_f32 v157, v9, v24
	v_cvt_pk_bf16_f32 v158, v11, v26
	v_cvt_pk_bf16_f32 v159, v13, v28
	v_cvt_pk_bf16_f32 v148, v43, v16
	v_cvt_pk_bf16_f32 v149, v17, v2
	v_cvt_pk_bf16_f32 v150, v39, v4
	v_cvt_pk_bf16_f32 v151, v19, v6
	v_cvt_pk_bf16_f32 v160, v21, v8
	v_cvt_pk_bf16_f32 v161, v23, v10
	v_cvt_pk_bf16_f32 v162, v25, v12
	v_cvt_pk_bf16_f32 v163, v27, v14
	s_cmp_lt_i32 s82, 2
	v_xor_b32_e32 v236, 0x80, v235
	v_xor_b32_e32 v234, 0xc0, v235
	s_cbranch_scc1 .LBB0_331
	s_mov_b32 s97, s83
	s_lshl_b64 s[0:1], s[96:97], 13
	v_lshl_add_u64 v[0:1], v[212:213], 0, s[0:1]
	s_mov_b64 s[0:1], 0x106000
	v_lshl_add_u64 v[218:219], v[0:1], 0, s[0:1]
	s_mov_b64 s[0:1], 0x6000
	v_lshl_add_u64 v[220:221], v[0:1], 0, s[0:1]
	s_lshl_b64 s[0:1], s[96:97], 14
	v_lshl_add_u64 v[0:1], v[214:215], 0, s[0:1]
	s_mov_b64 s[4:5], 0xc000
	v_lshl_add_u64 v[222:223], v[0:1], 0, s[4:5]
	v_lshl_add_u64 v[0:1], v[216:217], 0, s[0:1]
	v_readlane_b32 s1, v244, 25
	s_add_i32 s1, s1, s2
	v_lshl_add_u64 v[224:225], v[0:1], 0, s[4:5]
	v_add_u32_e32 v0, s1, v32
	s_lshl_b32 s0, s96, 6
	v_sub_u32_e32 v0, v0, v34
	s_add_i32 s97, s0, 0x7f
	v_subrev_u32_e32 v240, s0, v0
	s_and_b32 s0, s74, 63
	s_lshl_b32 s0, s0, 7
	v_mov_b32_e32 v0, 0
	v_mul_f32_e32 v237, 0x42000000, v208
	v_add_u32_e32 v238, 0, v36
	v_xor_b32_e32 v239, 64, v235
	s_add_i32 s73, s33, -2
	s_add_i32 s79, s77, 0x18000
	s_sub_i32 s74, 0, s0
	v_mov_b32_e32 v1, v0
	v_mov_b32_e32 v2, v0
	v_mov_b32_e32 v3, v0
	v_mov_b32_e32 v4, v0
	v_mov_b32_e32 v5, v0
	v_mov_b32_e32 v6, v0
	v_mov_b32_e32 v7, v0
	v_mov_b32_e32 v8, v0
	v_mov_b32_e32 v9, v0
	v_mov_b32_e32 v10, v0
	v_mov_b32_e32 v11, v0
	v_mov_b32_e32 v12, v0
	v_mov_b32_e32 v13, v0
	v_mov_b32_e32 v14, v0
	v_mov_b32_e32 v15, v0
	v_mov_b32_e32 v16, v0
	v_mov_b32_e32 v17, v0
	v_mov_b32_e32 v18, v0
	v_mov_b32_e32 v19, v0
	v_mov_b32_e32 v20, v0
	v_mov_b32_e32 v21, v0
	v_mov_b32_e32 v22, v0
	v_mov_b32_e32 v23, v0
	v_mov_b32_e32 v24, v0
	v_mov_b32_e32 v25, v0
	v_mov_b32_e32 v26, v0
	v_mov_b32_e32 v27, v0
	v_mov_b32_e32 v28, v0
	v_mov_b32_e32 v29, v0
	v_mov_b32_e32 v30, v0
	v_mov_b32_e32 v31, v0
	v_mov_b32_e32 v32, v0
	v_mov_b32_e32 v33, v0
	v_mov_b32_e32 v34, v0
	v_mov_b32_e32 v35, v0
	v_mov_b32_e32 v36, v0
	v_mov_b32_e32 v37, v0
	v_mov_b32_e32 v38, v0
	v_mov_b32_e32 v39, v0
	v_mov_b32_e32 v40, v0
	v_mov_b32_e32 v41, v0
	v_mov_b32_e32 v42, v0
	v_mov_b32_e32 v43, v0
	v_mov_b32_e32 v44, v0
	v_mov_b32_e32 v45, v0
	v_mov_b32_e32 v46, v0
	v_mov_b32_e32 v47, v0
	v_mov_b32_e32 v48, v0
	v_mov_b32_e32 v49, v0
	v_mov_b32_e32 v50, v0
	v_mov_b32_e32 v51, v0
	v_mov_b32_e32 v52, v0
	v_mov_b32_e32 v53, v0
	v_mov_b32_e32 v54, v0
	v_mov_b32_e32 v55, v0
	v_mov_b32_e32 v56, v0
	v_mov_b32_e32 v57, v0
	v_mov_b32_e32 v58, v0
	v_mov_b32_e32 v59, v0
	v_mov_b32_e32 v60, v0
	v_mov_b32_e32 v61, v0
	v_mov_b32_e32 v62, v0
	v_mov_b32_e32 v63, v0
	v_add_u32_e32 v222, v238, v230
	v_add_u32_e32 v223, v238, v231
	v_add_u32_e32 v241, v238, v232
	v_add_u32_e32 v242, v238, v233
	s_sub_i32 s101, s78, s97
	s_ashr_i32 s101, s101, 6
	s_add_i32 s98, s33, -3
	s_add_i32 s99, s82, -1
	s_add_i32 s100, s74, s97
	s_sub_i32 s100, s100, 63
	v_mov_b32_e32 v166, v160
	v_mov_b32_e32 v167, v161
	v_mov_b32_e32 v168, v162
	v_mov_b32_e32 v169, v163
	v_mov_b32_e32 v162, v156
	v_mov_b32_e32 v163, v157
	v_mov_b32_e32 v164, v158
	v_mov_b32_e32 v165, v159
	v_mov_b32_e32 v174, v152
	v_mov_b32_e32 v175, v153
	v_mov_b32_e32 v176, v154
	v_mov_b32_e32 v177, v155
	v_mov_b32_e32 v170, v148
	v_mov_b32_e32 v171, v149
	v_mov_b32_e32 v172, v150
	v_mov_b32_e32 v173, v151
	v_cvt_f32_i32_e32 v156, s100
	v_add_f32_e32 v156, v255, v156
	v_fma_f32 v254, v208, v156, -v207
	v_mov_b32_e32 v64, v254
	v_fmamk_f32 v65, v208, 0x3f800000, v254
	v_fmamk_f32 v66, v208, 0x40000000, v254
	v_fmamk_f32 v67, v208, 0x40400000, v254
	v_fmamk_f32 v68, v208, 0x41000000, v254
	v_fmamk_f32 v69, v208, 0x41100000, v254
	v_fmamk_f32 v70, v208, 0x41200000, v254
	v_fmamk_f32 v71, v208, 0x41300000, v254
	v_fmamk_f32 v72, v208, 0x41800000, v254
	v_fmamk_f32 v73, v208, 0x41880000, v254
	v_fmamk_f32 v74, v208, 0x41900000, v254
	v_fmamk_f32 v75, v208, 0x41980000, v254
	v_fmamk_f32 v76, v208, 0x41c00000, v254
	v_fmamk_f32 v77, v208, 0x41c80000, v254
	v_fmamk_f32 v78, v208, 0x41d00000, v254
	v_fmamk_f32 v79, v208, 0x41d80000, v254
	s_cmp_ge_i32 s72, s73
	s_mov_b64 s[0:1], -1
	s_cbranch_scc0 .LBB0_321

.Lk_top:
	ds_read_b128 v[80:83], v158 offset:16384
	ds_read_b128 v[202:205], v159 offset:16384
	ds_read_b128 v[194:197], v160 offset:16384
	ds_read_b128 v[186:189], v161 offset:16384
	ds_read_b128 v[198:201], v158 offset:20480
	ds_read_b128 v[190:193], v159 offset:20480
	ds_read_b128 v[246:249], v160 offset:20480
	ds_read_b128 v[250:253], v161 offset:20480
	s_cmp_ge_i32 s72, s98
	s_cbranch_scc1 .LBB0_325
	s_add_i32 m0, s1, s94
	s_add_i32 s4, s90, s1
	global_load_lds_dwordx4 v[220:221], off
	s_mov_b32 m0, s4
	s_add_i32 s4, s1, s66
	global_load_lds_dwordx4 v[218:219], off
	s_mov_b32 m0, s4
	global_load_lds_dwordx4 v[224:225], off
	global_load_lds_dwordx4 v[224:225], off offset:1024
.LBB0_325:
	s_waitcnt lgkmcnt(4)
	v_mfma_f32_32x32x16_bf16 v[96:111], v[80:83], v[144:147], v[64:79]
	v_mfma_f32_32x32x16_bf16 v[96:111], v[202:205], v[140:143], v[96:111]
	s_add_i32 s4, s100, 64
	v_cvt_f32_i32_e32 v156, s4
	v_add_f32_e32 v156, v255, v156
	v_fma_f32 v254, v208, v156, -v207
	s_nop 0
	v_mfma_f32_32x32x16_bf16 v[96:111], v[194:197], v[136:139], v[96:111]
	v_mov_b32_e32 v64, v254
	v_fmamk_f32 v65, v208, 0x3f800000, v254
	v_fmamk_f32 v66, v208, 0x40000000, v254
	v_fmamk_f32 v67, v208, 0x40400000, v254
	v_fmamk_f32 v68, v208, 0x41000000, v254
	v_fmamk_f32 v69, v208, 0x41100000, v254
	v_fmamk_f32 v70, v208, 0x41200000, v254
	v_fmamk_f32 v71, v208, 0x41300000, v254
	v_mfma_f32_32x32x16_bf16 v[96:111], v[186:189], v[132:135], v[96:111]
	v_fmamk_f32 v72, v208, 0x41800000, v254
	v_fmamk_f32 v73, v208, 0x41880000, v254
	v_fmamk_f32 v74, v208, 0x41900000, v254
	v_fmamk_f32 v75, v208, 0x41980000, v254
	v_fmamk_f32 v76, v208, 0x41c00000, v254
	v_fmamk_f32 v77, v208, 0x41c80000, v254
	v_fmamk_f32 v78, v208, 0x41d00000, v254
	v_fmamk_f32 v79, v208, 0x41d80000, v254
	s_add_i32 s3, s79, 0xfffe8000
	s_and_b32 s3, s3, 0x18000
	v_add_u32_e32 v158, s3, v235
	v_add_u32_e32 v159, s3, v239
	v_add_u32_e32 v160, s3, v236
	v_add_u32_e32 v161, s3, v234
	ds_read_b64_tr_b16 v[182:183], v158 offset:32768
	ds_read_b64_tr_b16 v[184:185], v158 offset:34816
	ds_read_b64_tr_b16 v[178:179], v159 offset:32768
	ds_read_b64_tr_b16 v[180:181], v159 offset:34816
	ds_read_b64_tr_b16 v[148:149], v160 offset:32768
	ds_read_b64_tr_b16 v[150:151], v160 offset:34816
	ds_read_b64_tr_b16 v[152:153], v161 offset:32768
	ds_read_b64_tr_b16 v[154:155], v161 offset:34816
	s_waitcnt lgkmcnt(8)
	v_mfma_f32_32x32x16_bf16 v[80:95], v[198:201], v[144:147], v[64:79]
	v_exp_f32_e32 v96, v96
	v_exp_f32_e32 v97, v97
	v_exp_f32_e32 v98, v98
	v_exp_f32_e32 v99, v99
	v_mfma_f32_32x32x16_bf16 v[80:95], v[190:193], v[140:143], v[80:95]
	v_exp_f32_e32 v100, v100
	v_exp_f32_e32 v101, v101
	v_exp_f32_e32 v102, v102
	v_exp_f32_e32 v103, v103
	v_mfma_f32_32x32x16_bf16 v[80:95], v[246:249], v[136:139], v[80:95]
	v_exp_f32_e32 v104, v104
	v_exp_f32_e32 v105, v105
	v_exp_f32_e32 v106, v106
	v_exp_f32_e32 v107, v107
	v_mfma_f32_32x32x16_bf16 v[80:95], v[250:253], v[132:135], v[80:95]
	v_exp_f32_e32 v108, v108
	v_exp_f32_e32 v109, v109
	v_exp_f32_e32 v110, v110
	v_exp_f32_e32 v111, v111
	s_nop 3
	s_cmp_le_i32 s72, s101
	s_cbranch_scc0 .Lmask_blk
.LBB0_327:
	s_waitcnt lgkmcnt(4)
	v_mfma_f32_32x32x16_bf16 v[48:63], v[182:185], v[174:177], v[48:63]
	v_sub_f32_e32 v190, v80, v237
	v_exp_f32_e32 v190, v190
	ds_read_b64_tr_b16 v[246:247], v158 offset:36864
	ds_read_b64_tr_b16 v[248:249], v158 offset:38912
	v_add_f32_e32 v157, v190, v96
	v_mfma_f32_32x32x16_bf16 v[32:47], v[178:181], v[174:177], v[32:47]
	v_sub_f32_e32 v191, v81, v237
	v_exp_f32_e32 v191, v191
	ds_read_b64_tr_b16 v[250:251], v159 offset:36864
	ds_read_b64_tr_b16 v[252:253], v159 offset:38912
	v_add_f32_e32 v156, v191, v97
	v_add_f32_e32 v157, v156, v157
	s_waitcnt lgkmcnt(4)
	v_mfma_f32_32x32x16_bf16 v[16:31], v[148:151], v[174:177], v[16:31]
	v_sub_f32_e32 v192, v82, v237
	v_exp_f32_e32 v192, v192
	ds_read_b64_tr_b16 v[182:183], v160 offset:36864
	ds_read_b64_tr_b16 v[184:185], v160 offset:38912
	v_add_f32_e32 v156, v192, v98
	v_add_f32_e32 v157, v156, v157
	v_mfma_f32_32x32x16_bf16 v[0:15], v[152:155], v[174:177], v[0:15]
	v_sub_f32_e32 v193, v83, v237
	v_exp_f32_e32 v193, v193
	ds_read_b64_tr_b16 v[178:179], v161 offset:36864
	ds_read_b64_tr_b16 v[180:181], v161 offset:38912
	v_add_f32_e32 v156, v193, v99
	v_add_f32_e32 v157, v156, v157
	v_cvt_pk_bf16_f32 v174, v96, v97
	s_waitcnt lgkmcnt(4)
	v_mfma_f32_32x32x16_bf16 v[48:63], v[246:249], v[162:165], v[48:63]
	v_sub_f32_e32 v194, v84, v237
	v_exp_f32_e32 v194, v194
	ds_read_b64_tr_b16 v[148:149], v158 offset:40960
	ds_read_b64_tr_b16 v[150:151], v158 offset:43008
	v_add_f32_e32 v156, v194, v100
	v_add_f32_e32 v157, v156, v157
	v_cvt_pk_bf16_f32 v175, v98, v99
	v_mfma_f32_32x32x16_bf16 v[32:47], v[250:253], v[162:165], v[32:47]
	v_sub_f32_e32 v195, v85, v237
	v_exp_f32_e32 v195, v195
	ds_read_b64_tr_b16 v[152:153], v159 offset:40960
	ds_read_b64_tr_b16 v[154:155], v159 offset:43008
	v_add_f32_e32 v156, v195, v101
	v_add_f32_e32 v157, v156, v157
	v_cvt_pk_bf16_f32 v176, v100, v101
	s_waitcnt lgkmcnt(4)
	v_mfma_f32_32x32x16_bf16 v[16:31], v[182:185], v[162:165], v[16:31]
	v_sub_f32_e32 v196, v86, v237
	v_exp_f32_e32 v196, v196
	ds_read_b64_tr_b16 v[246:247], v160 offset:40960
	ds_read_b64_tr_b16 v[248:249], v160 offset:43008
	v_add_f32_e32 v156, v196, v102
	v_add_f32_e32 v157, v156, v157
	v_cvt_pk_bf16_f32 v177, v102, v103
	v_mfma_f32_32x32x16_bf16 v[0:15], v[178:181], v[162:165], v[0:15]
	v_sub_f32_e32 v197, v87, v237
	v_exp_f32_e32 v197, v197
	ds_read_b64_tr_b16 v[250:251], v161 offset:40960
	ds_read_b64_tr_b16 v[252:253], v161 offset:43008
	v_add_f32_e32 v156, v197, v103
	v_add_f32_e32 v157, v156, v157
	v_cvt_pk_bf16_f32 v162, v104, v105
	s_waitcnt lgkmcnt(4)
	v_mfma_f32_32x32x16_bf16 v[48:63], v[148:151], v[170:173], v[48:63]
	v_sub_f32_e32 v198, v88, v237
	v_exp_f32_e32 v198, v198
	ds_read_b64_tr_b16 v[182:183], v158 offset:45056
	ds_read_b64_tr_b16 v[184:185], v158 offset:47104
	v_add_f32_e32 v156, v198, v104
	v_add_f32_e32 v157, v156, v157
	v_cvt_pk_bf16_f32 v163, v106, v107
	v_mfma_f32_32x32x16_bf16 v[32:47], v[152:155], v[170:173], v[32:47]
	v_sub_f32_e32 v199, v89, v237
	v_exp_f32_e32 v199, v199
	ds_read_b64_tr_b16 v[178:179], v159 offset:45056
	ds_read_b64_tr_b16 v[180:181], v159 offset:47104
	v_add_f32_e32 v156, v199, v105
	v_add_f32_e32 v157, v156, v157
	v_cvt_pk_bf16_f32 v164, v108, v109
	s_waitcnt lgkmcnt(4)
	v_mfma_f32_32x32x16_bf16 v[16:31], v[246:249], v[170:173], v[16:31]
	v_sub_f32_e32 v200, v90, v237
	v_exp_f32_e32 v200, v200
	ds_read_b64_tr_b16 v[148:149], v160 offset:45056
	ds_read_b64_tr_b16 v[150:151], v160 offset:47104
	v_add_f32_e32 v156, v200, v106
	v_add_f32_e32 v157, v156, v157
	v_cvt_pk_bf16_f32 v165, v110, v111
	v_mfma_f32_32x32x16_bf16 v[0:15], v[250:253], v[170:173], v[0:15]
	v_sub_f32_e32 v201, v91, v237
	v_exp_f32_e32 v201, v201
	ds_read_b64_tr_b16 v[152:153], v161 offset:45056
	ds_read_b64_tr_b16 v[154:155], v161 offset:47104
	v_add_f32_e32 v156, v201, v107
	v_add_f32_e32 v157, v156, v157
	v_cvt_pk_bf16_f32 v170, v190, v191
	s_waitcnt lgkmcnt(4)
	v_mfma_f32_32x32x16_bf16 v[48:63], v[182:185], v[166:169], v[48:63]
	v_sub_f32_e32 v202, v92, v237
	v_exp_f32_e32 v202, v202
	v_cvt_pk_bf16_f32 v171, v192, v193
	v_add_f32_e32 v156, v202, v108
	v_add_f32_e32 v157, v156, v157
	v_mfma_f32_32x32x16_bf16 v[32:47], v[178:181], v[166:169], v[32:47]
	v_sub_f32_e32 v203, v93, v237
	v_exp_f32_e32 v203, v203
	v_cvt_pk_bf16_f32 v172, v194, v195
	v_add_f32_e32 v156, v203, v109
	v_add_f32_e32 v157, v156, v157
	s_waitcnt lgkmcnt(0)
	v_mfma_f32_32x32x16_bf16 v[16:31], v[148:151], v[166:169], v[16:31]
	v_sub_f32_e32 v204, v94, v237
	v_exp_f32_e32 v204, v204
	v_cvt_pk_bf16_f32 v173, v196, v197
	v_add_f32_e32 v156, v204, v110
	v_add_f32_e32 v157, v156, v157
	v_mfma_f32_32x32x16_bf16 v[0:15], v[152:155], v[166:169], v[0:15]
	v_sub_f32_e32 v205, v95, v237
	v_exp_f32_e32 v205, v205
	v_cvt_pk_bf16_f32 v166, v198, v199
	v_add_f32_e32 v156, v205, v111
	v_add_f32_e32 v157, v156, v157
	v_cvt_pk_bf16_f32 v167, v200, v201
	v_cvt_pk_bf16_f32 v168, v202, v203
	v_cvt_pk_bf16_f32 v169, v204, v205
	s_add_i32 s72, s72, 1
	s_add_i32 s79, s79, 0x8000
	s_add_i32 s100, s100, 64
	v_add_f32_e32 v229, v229, v157
	v_lshl_add_u64 v[218:219], v[218:219], 0, s[88:89]
	v_lshl_add_u64 v[220:221], v[220:221], 0, s[88:89]
	v_lshl_add_u64 v[224:225], v[224:225], 0, s[92:93]
	s_and_b32 s1, s79, 0x18000
	s_xor_b32 s0, s1, 0x10000
	v_add_u32_e32 v158, s0, v222
	v_add_u32_e32 v159, s0, v223
	v_add_u32_e32 v160, s0, v241
	v_add_u32_e32 v161, s0, v242
	s_cmp_ge_i32 s72, s99
	s_cbranch_scc1 .LBB0_332
	s_cmp_ge_i32 s72, s73
	s_cbranch_scc1 .Lk_last
	s_waitcnt vmcnt(4) lgkmcnt(0)
	s_barrier
	s_branch .Lk_top
